# ssd_scan2: removed the full vmcnt(0) drain in the middle of each 32-load batch (early unpacks sunk below the last load, vmcnt(15) instead)
# speedup vs baseline: 1.0007x; 1.0007x over previous
.LBB0_588:
	s_add_i32 s21, s20, 15
	v_mov_b32_e32 v8, s21
	v_mov_b32_e32 v10, s3
	v_cndmask_b32_e32 v8, v8, v10, vcc
	v_add_u32_e32 v10, v8, v9
	v_ashrrev_i32_e32 v11, 31, v10
	v_lshlrev_b64 v[14:15], 4, v[10:11]
	v_or_b32_e32 v14, v14, v0
	v_lshlrev_b64 v[12:13], 13, v[14:15]
	v_lshl_add_u64 v[12:13], v[2:3], 0, v[12:13]
	v_lshl_add_u64 v[14:15], v[14:15], 2, s[38:39]
	s_add_i32 s21, s20, 14
	s_add_i32 s22, s3, 1
	global_load_dword v13, v[12:13], off
	v_lshlrev_b64 v[10:11], 17, v[10:11]
	global_load_dword v8, v[14:15], off
	v_mov_b32_e32 v12, s21
	v_mov_b32_e32 v14, s22
	v_cndmask_b32_e32 v12, v12, v14, vcc
	v_add_u32_e32 v14, v12, v9
	v_ashrrev_i32_e32 v15, 31, v14
	v_lshlrev_b64 v[18:19], 4, v[14:15]
	v_or_b32_e32 v18, v18, v0
	v_lshlrev_b64 v[16:17], 13, v[18:19]
	v_lshl_add_u64 v[16:17], v[2:3], 0, v[16:17]
	v_lshl_add_u64 v[18:19], v[18:19], 2, s[38:39]
	s_add_i32 s21, s20, 13
	s_add_i32 s22, s3, 2
	global_load_dword v17, v[16:17], off
	v_lshl_add_u64 v[10:11], v[4:5], 0, v[10:11]
	global_load_dword v12, v[18:19], off
	v_mov_b32_e32 v16, s21
	v_mov_b32_e32 v18, s22
	v_cndmask_b32_e32 v16, v16, v18, vcc
	v_add_u32_e32 v18, v16, v9
	v_ashrrev_i32_e32 v19, 31, v18
	v_lshlrev_b64 v[22:23], 4, v[18:19]
	v_or_b32_e32 v22, v22, v0
	v_lshlrev_b64 v[20:21], 13, v[22:23]
	v_lshl_add_u64 v[20:21], v[2:3], 0, v[20:21]
	v_lshl_add_u64 v[22:23], v[22:23], 2, s[38:39]
	s_add_i32 s21, s20, 12
	s_add_i32 s22, s3, 3
	global_load_dword v21, v[20:21], off
	v_lshlrev_b64 v[14:15], 17, v[14:15]
	global_load_dword v16, v[22:23], off
	v_mov_b32_e32 v20, s21
	v_mov_b32_e32 v22, s22
	v_cndmask_b32_e32 v20, v20, v22, vcc
	v_add_u32_e32 v22, v20, v9
	v_ashrrev_i32_e32 v23, 31, v22
	v_lshlrev_b64 v[26:27], 4, v[22:23]
	v_or_b32_e32 v26, v26, v0
	v_lshlrev_b64 v[24:25], 13, v[26:27]
	v_lshl_add_u64 v[24:25], v[2:3], 0, v[24:25]
	v_lshl_add_u64 v[26:27], v[26:27], 2, s[38:39]
	s_add_i32 s21, s20, 11
	s_add_i32 s22, s3, 4
	global_load_dword v25, v[24:25], off
	v_lshl_add_u64 v[14:15], v[4:5], 0, v[14:15]
	global_load_dword v20, v[26:27], off
	v_mov_b32_e32 v24, s21
	v_mov_b32_e32 v26, s22
	v_cndmask_b32_e32 v24, v24, v26, vcc
	v_add_u32_e32 v26, v24, v9
	v_ashrrev_i32_e32 v27, 31, v26
	v_lshlrev_b64 v[30:31], 4, v[26:27]
	v_or_b32_e32 v30, v30, v0
	v_lshlrev_b64 v[28:29], 13, v[30:31]
	v_lshl_add_u64 v[28:29], v[2:3], 0, v[28:29]
	v_lshl_add_u64 v[30:31], v[30:31], 2, s[38:39]
	s_add_i32 s21, s20, 10
	s_add_i32 s22, s3, 5
	global_load_dword v29, v[28:29], off
	v_lshlrev_b64 v[18:19], 17, v[18:19]
	global_load_dword v24, v[30:31], off
	v_mov_b32_e32 v28, s21
	v_mov_b32_e32 v30, s22
	v_cndmask_b32_e32 v28, v28, v30, vcc
	v_add_u32_e32 v30, v28, v9
	v_ashrrev_i32_e32 v31, 31, v30
	v_lshlrev_b64 v[34:35], 4, v[30:31]
	v_or_b32_e32 v34, v34, v0
	v_lshlrev_b64 v[32:33], 13, v[34:35]
	v_lshl_add_u64 v[32:33], v[2:3], 0, v[32:33]
	v_lshl_add_u64 v[34:35], v[34:35], 2, s[38:39]
	s_add_i32 s21, s20, 9
	s_add_i32 s22, s3, 6
	global_load_dword v33, v[32:33], off
	v_lshl_add_u64 v[18:19], v[4:5], 0, v[18:19]
	global_load_dword v28, v[34:35], off
	v_mov_b32_e32 v32, s21
	v_mov_b32_e32 v34, s22
	v_cndmask_b32_e32 v32, v32, v34, vcc
	v_add_u32_e32 v34, v32, v9
	v_ashrrev_i32_e32 v35, 31, v34
	v_lshlrev_b64 v[38:39], 4, v[34:35]
	v_or_b32_e32 v38, v38, v0
	v_lshlrev_b64 v[36:37], 13, v[38:39]
	v_lshl_add_u64 v[36:37], v[2:3], 0, v[36:37]
	v_lshl_add_u64 v[38:39], v[38:39], 2, s[38:39]
	s_add_i32 s21, s20, 8
	s_add_i32 s22, s3, 7
	global_load_dword v37, v[36:37], off
	v_lshlrev_b64 v[22:23], 17, v[22:23]
	global_load_dword v32, v[38:39], off
	v_mov_b32_e32 v36, s21
	v_mov_b32_e32 v38, s22
	v_cndmask_b32_e32 v36, v36, v38, vcc
	v_add_u32_e32 v38, v36, v9
	v_ashrrev_i32_e32 v39, 31, v38
	v_lshlrev_b64 v[42:43], 4, v[38:39]
	v_or_b32_e32 v42, v42, v0
	v_lshlrev_b64 v[40:41], 13, v[42:43]
	v_lshl_add_u64 v[40:41], v[2:3], 0, v[40:41]
	v_lshl_add_u64 v[42:43], v[42:43], 2, s[38:39]
	s_add_i32 s21, s20, 7
	s_add_i32 s22, s3, 8
	global_load_dword v41, v[40:41], off
	v_lshl_add_u64 v[22:23], v[4:5], 0, v[22:23]
	global_load_dword v36, v[42:43], off
	v_mov_b32_e32 v40, s21
	v_mov_b32_e32 v42, s22
	v_cndmask_b32_e32 v40, v40, v42, vcc
	v_add_u32_e32 v42, v40, v9
	v_ashrrev_i32_e32 v43, 31, v42
	v_lshlrev_b64 v[46:47], 4, v[42:43]
	v_or_b32_e32 v46, v46, v0
	v_lshlrev_b64 v[44:45], 13, v[46:47]
	v_lshl_add_u64 v[44:45], v[2:3], 0, v[44:45]
	v_lshl_add_u64 v[46:47], v[46:47], 2, s[38:39]
	s_add_i32 s21, s20, 6
	s_add_i32 s22, s3, 9
	global_load_dword v45, v[44:45], off
	global_load_dword v40, v[46:47], off
	v_mov_b32_e32 v44, s21
	v_mov_b32_e32 v46, s22
	v_cndmask_b32_e32 v44, v44, v46, vcc
	v_add_u32_e32 v46, v44, v9
	v_ashrrev_i32_e32 v47, 31, v46
	v_lshlrev_b64 v[50:51], 4, v[46:47]
	v_or_b32_e32 v50, v50, v0
	v_lshlrev_b64 v[48:49], 13, v[50:51]
	v_lshl_add_u64 v[48:49], v[2:3], 0, v[48:49]
	v_lshl_add_u64 v[50:51], v[50:51], 2, s[38:39]
	s_add_i32 s21, s20, 5
	s_add_i32 s22, s3, 10
	global_load_dword v49, v[48:49], off
	global_load_dword v44, v[50:51], off
	v_mov_b32_e32 v48, s21
	v_mov_b32_e32 v50, s22
	v_cndmask_b32_e32 v48, v48, v50, vcc
	v_add_u32_e32 v50, v48, v9
	v_ashrrev_i32_e32 v51, 31, v50
	v_lshlrev_b64 v[54:55], 4, v[50:51]
	v_or_b32_e32 v54, v54, v0
	v_lshlrev_b64 v[52:53], 13, v[54:55]
	v_lshl_add_u64 v[52:53], v[2:3], 0, v[52:53]
	v_lshl_add_u64 v[54:55], v[54:55], 2, s[38:39]
	s_add_i32 s21, s20, 4
	s_add_i32 s22, s3, 11
	global_load_dword v53, v[52:53], off
	global_load_dword v48, v[54:55], off
	v_mov_b32_e32 v52, s21
	v_mov_b32_e32 v54, s22
	v_cndmask_b32_e32 v52, v52, v54, vcc
	v_add_u32_e32 v54, v52, v9
	v_ashrrev_i32_e32 v55, 31, v54
	v_lshlrev_b64 v[56:57], 4, v[54:55]
	v_or_b32_e32 v56, v56, v0
	v_lshlrev_b64 v[58:59], 13, v[56:57]
	v_lshl_add_u64 v[58:59], v[2:3], 0, v[58:59]
	v_lshl_add_u64 v[56:57], v[56:57], 2, s[38:39]
	s_add_i32 s21, s20, 3
	s_add_i32 s22, s3, 12
	global_load_dword v80, v[58:59], off
	global_load_dword v52, v[56:57], off
	v_mov_b32_e32 v56, s21
	v_mov_b32_e32 v57, s22
	v_cndmask_b32_e32 v56, v56, v57, vcc
	v_add_u32_e32 v58, v56, v9
	v_ashrrev_i32_e32 v59, 31, v58
	v_lshlrev_b64 v[56:57], 4, v[58:59]
	v_or_b32_e32 v56, v56, v0
	v_lshlrev_b64 v[60:61], 13, v[56:57]
	v_lshl_add_u64 v[60:61], v[2:3], 0, v[60:61]
	v_lshl_add_u64 v[56:57], v[56:57], 2, s[38:39]
	s_add_i32 s21, s20, 2
	s_add_i32 s22, s3, 13
	global_load_dword v81, v[60:61], off
	global_load_dword v56, v[56:57], off
	v_mov_b32_e32 v57, s21
	v_mov_b32_e32 v60, s22
	v_cndmask_b32_e32 v57, v57, v60, vcc
	v_add_u32_e32 v62, v57, v9
	v_ashrrev_i32_e32 v63, 31, v62
	v_lshlrev_b64 v[60:61], 4, v[62:63]
	v_or_b32_e32 v60, v60, v0
	v_lshlrev_b64 v[64:65], 13, v[60:61]
	v_lshl_add_u64 v[64:65], v[2:3], 0, v[64:65]
	v_lshl_add_u64 v[60:61], v[60:61], 2, s[38:39]
	s_add_i32 s21, s20, 1
	s_add_i32 s22, s3, 14
	global_load_dword v57, v[64:65], off
	v_lshlrev_b64 v[26:27], 17, v[26:27]
	global_load_dword v60, v[60:61], off
	v_mov_b32_e32 v61, s21
	v_mov_b32_e32 v64, s22
	v_cndmask_b32_e32 v61, v61, v64, vcc
	v_add_u32_e32 v66, v61, v9
	v_ashrrev_i32_e32 v67, 31, v66
	v_lshlrev_b64 v[64:65], 4, v[66:67]
	v_or_b32_e32 v64, v64, v0
	v_lshlrev_b64 v[68:69], 13, v[64:65]
	v_lshl_add_u64 v[68:69], v[2:3], 0, v[68:69]
	v_lshl_add_u64 v[64:65], v[64:65], 2, s[38:39]
	s_add_i32 s21, s3, 15
	global_load_dword v61, v[68:69], off
	global_load_dword v64, v[64:65], off
	v_mov_b32_e32 v65, s20
	v_mov_b32_e32 v68, s21
	v_cndmask_b32_e32 v65, v65, v68, vcc
	v_add_u32_e32 v68, v65, v9
	v_ashrrev_i32_e32 v69, 31, v68
	v_lshlrev_b64 v[70:71], 4, v[68:69]
	v_or_b32_e32 v70, v70, v0
	v_lshlrev_b64 v[72:73], 13, v[70:71]
	v_lshl_add_u64 v[72:73], v[2:3], 0, v[72:73]
	global_load_dword v65, v[72:73], off
	v_lshl_add_u64 v[70:71], v[70:71], 2, s[38:39]
	global_load_dword v70, v[70:71], off
	s_waitcnt vmcnt(15)
	v_lshlrev_b32_e32 v74, 16, v21
	v_and_b32_e32 v75, 0xffff0000, v21
	v_lshlrev_b32_e32 v76, 16, v25
	v_and_b32_e32 v77, 0xffff0000, v25
	v_lshlrev_b32_e32 v78, 16, v29
	v_cvt_pk_bf16_f32 v71, v6, v7
	global_store_dword v[10:11], v71, off
	v_lshlrev_b32_e32 v10, 16, v13
	v_and_b32_e32 v11, 0xffff0000, v13
	v_pk_fma_f32 v[6:7], v[6:7], v[8:9], v[10:11] op_sel_hi:[1,0,1]
	v_lshlrev_b32_e32 v72, 16, v17
	v_and_b32_e32 v73, 0xffff0000, v17
	v_cvt_pk_bf16_f32 v8, v6, v7
	v_pk_fma_f32 v[6:7], v[6:7], v[12:13], v[72:73] op_sel_hi:[1,0,1]
	global_store_dword v[14:15], v8, off
	v_cvt_pk_bf16_f32 v8, v6, v7
	v_pk_fma_f32 v[6:7], v[6:7], v[16:17], v[74:75] op_sel_hi:[1,0,1]
	global_store_dword v[18:19], v8, off
	v_cvt_pk_bf16_f32 v8, v6, v7
	v_pk_fma_f32 v[6:7], v[6:7], v[20:21], v[76:77] op_sel_hi:[1,0,1]
	global_store_dword v[22:23], v8, off
	v_and_b32_e32 v79, 0xffff0000, v29
	v_lshl_add_u64 v[26:27], v[4:5], 0, v[26:27]
	v_cvt_pk_bf16_f32 v8, v6, v7
	v_pk_fma_f32 v[6:7], v[6:7], v[24:25], v[78:79] op_sel_hi:[1,0,1]
	global_store_dword v[26:27], v8, off
	v_cvt_pk_bf16_f32 v8, v6, v7
	v_lshlrev_b64 v[10:11], 17, v[30:31]
	v_lshl_add_u64 v[10:11], v[4:5], 0, v[10:11]
	global_store_dword v[10:11], v8, off
	v_lshlrev_b32_e32 v10, 16, v33
	v_and_b32_e32 v11, 0xffff0000, v33
	v_pk_fma_f32 v[6:7], v[6:7], v[28:29], v[10:11] op_sel_hi:[1,0,1]
	v_lshlrev_b64 v[12:13], 17, v[34:35]
	v_lshlrev_b32_e32 v14, 16, v37
	v_and_b32_e32 v15, 0xffff0000, v37
	v_lshl_add_u64 v[12:13], v[4:5], 0, v[12:13]
	v_cvt_pk_bf16_f32 v8, v6, v7
	v_pk_fma_f32 v[6:7], v[6:7], v[32:33], v[14:15] op_sel_hi:[1,0,1]
	global_store_dword v[12:13], v8, off
	v_lshlrev_b64 v[16:17], 17, v[38:39]
	v_lshlrev_b32_e32 v18, 16, v41
	v_and_b32_e32 v19, 0xffff0000, v41
	v_lshl_add_u64 v[16:17], v[4:5], 0, v[16:17]
	v_cvt_pk_bf16_f32 v8, v6, v7
	v_pk_fma_f32 v[6:7], v[6:7], v[36:37], v[18:19] op_sel_hi:[1,0,1]
	global_store_dword v[16:17], v8, off
	v_lshlrev_b64 v[20:21], 17, v[42:43]
	v_lshlrev_b32_e32 v22, 16, v45
	v_and_b32_e32 v23, 0xffff0000, v45
	v_lshl_add_u64 v[20:21], v[4:5], 0, v[20:21]
	v_cvt_pk_bf16_f32 v8, v6, v7
	s_waitcnt vmcnt(22)
	v_pk_fma_f32 v[6:7], v[6:7], v[40:41], v[22:23] op_sel_hi:[1,0,1]
	global_store_dword v[20:21], v8, off
	v_lshlrev_b64 v[24:25], 17, v[46:47]
	s_waitcnt vmcnt(22)
	v_lshlrev_b32_e32 v26, 16, v49
	v_and_b32_e32 v27, 0xffff0000, v49
	v_lshl_add_u64 v[24:25], v[4:5], 0, v[24:25]
	v_cvt_pk_bf16_f32 v8, v6, v7
	s_waitcnt vmcnt(21)
	v_pk_fma_f32 v[6:7], v[6:7], v[44:45], v[26:27] op_sel_hi:[1,0,1]
	global_store_dword v[24:25], v8, off
	v_lshlrev_b64 v[30:31], 17, v[50:51]
	s_waitcnt vmcnt(21)
	v_lshlrev_b32_e32 v34, 16, v53
	v_and_b32_e32 v35, 0xffff0000, v53
	v_lshl_add_u64 v[30:31], v[4:5], 0, v[30:31]
	v_cvt_pk_bf16_f32 v8, v6, v7
	s_waitcnt vmcnt(20)
	v_pk_fma_f32 v[6:7], v[6:7], v[48:49], v[34:35] op_sel_hi:[1,0,1]
	global_store_dword v[30:31], v8, off
	v_lshlrev_b64 v[10:11], 17, v[54:55]
	s_waitcnt vmcnt(20)
	v_lshlrev_b32_e32 v12, 16, v80
	v_and_b32_e32 v13, 0xffff0000, v80
	v_lshl_add_u64 v[10:11], v[4:5], 0, v[10:11]
	v_cvt_pk_bf16_f32 v8, v6, v7
	s_waitcnt vmcnt(19)
	v_pk_fma_f32 v[6:7], v[6:7], v[52:53], v[12:13] op_sel_hi:[1,0,1]
	global_store_dword v[10:11], v8, off
	v_lshlrev_b64 v[14:15], 17, v[58:59]
	s_waitcnt vmcnt(19)
	v_lshlrev_b32_e32 v16, 16, v81
	v_and_b32_e32 v17, 0xffff0000, v81
	v_lshl_add_u64 v[14:15], v[4:5], 0, v[14:15]
	v_cvt_pk_bf16_f32 v8, v6, v7
	s_waitcnt vmcnt(17)
	v_pk_fma_f32 v[6:7], v[6:7], v[56:57], v[16:17] op_sel_hi:[1,0,1]
	global_store_dword v[14:15], v8, off
	v_lshlrev_b64 v[18:19], 17, v[62:63]
	v_lshlrev_b32_e32 v20, 16, v57
	v_and_b32_e32 v21, 0xffff0000, v57
	v_lshl_add_u64 v[18:19], v[4:5], 0, v[18:19]
	v_cvt_pk_bf16_f32 v8, v6, v7
	s_waitcnt vmcnt(16)
	v_pk_fma_f32 v[6:7], v[6:7], v[60:61], v[20:21] op_sel_hi:[1,0,1]
	global_store_dword v[18:19], v8, off
	v_lshlrev_b64 v[22:23], 17, v[66:67]
	v_lshlrev_b32_e32 v24, 16, v61
	v_and_b32_e32 v25, 0xffff0000, v61
	v_lshl_add_u64 v[22:23], v[4:5], 0, v[22:23]
	v_cvt_pk_bf16_f32 v8, v6, v7
	s_waitcnt vmcnt(15)
	v_pk_fma_f32 v[6:7], v[6:7], v[64:65], v[24:25] op_sel_hi:[1,0,1]
	global_store_dword v[22:23], v8, off
	v_lshlrev_b64 v[26:27], 17, v[68:69]
	v_lshlrev_b32_e32 v28, 16, v65
	v_and_b32_e32 v29, 0xffff0000, v65
	s_add_i32 s20, s20, -16
	s_add_i32 s21, s3, 16
	v_lshl_add_u64 v[26:27], v[4:5], 0, v[26:27]
	v_cvt_pk_bf16_f32 v8, v6, v7
	s_waitcnt vmcnt(15)
	v_pk_fma_f32 v[6:7], v[6:7], v[70:71], v[28:29] op_sel_hi:[1,0,1]
	s_cmpk_lt_u32 s3, 0x70
	s_mov_b32 s3, s21
	global_store_dword v[26:27], v8, off
	s_cbranch_scc1 .LBB0_588
	v_add_u32_e32 v1, s2, v1
	s_mov_b32 s3, 0x3ffff
	v_cmp_lt_i32_e32 vcc, s3, v1
	s_or_b64 s[40:41], vcc, s[40:41]
	s_andn2_b64 exec, exec, s[40:41]
	s_cbranch_execnz .LBB0_587
